# helper priority raised only for the derive/M tail (PREP at normal priority)
# baseline (speedup 1.0000x reference)
.Lmy_f_nol34:
	s_waitcnt lgkmcnt(0)
	s_setprio 3
	s_bfe_u32 s96, s62, 0x20006
	s_lshl_b32 s100, s96, 11
	v_lshl_add_u32 v72, v224, 2, s100
	s_and_b32 s97, s96, 1
	s_mul_i32 s97, s97, 0x2700
	s_mov_b32 s101, 0x1c000
	s_mov_b32 s100, 0x6100
	s_bitcmp0_b32 s65, 0
	s_cselect_b32 s101, 0xe000, s101
	s_cselect_b32 s100, 0x4e00, s100
	s_cmp_gt_u32 s96, 1
	s_cselect_b32 s100, s100, 0
	s_add_i32 s97, s97, s101
	s_add_i32 s97, s97, s100
	ds_read_b32 v80, v72
	ds_read_b32 v81, v72 offset:256
	ds_read_b32 v82, v72 offset:512
	ds_read_b32 v83, v72 offset:768
	ds_read_b32 v84, v72 offset:1024
	ds_read_b32 v85, v72 offset:1280
	ds_read_b32 v86, v72 offset:1536
	ds_read_b32 v87, v72 offset:1792
	ds_read_b32 v88, v72 offset:8192
	ds_read_b32 v89, v72 offset:8448
	ds_read_b32 v90, v72 offset:8704
	ds_read_b32 v91, v72 offset:8960
	ds_read_b32 v92, v72 offset:9216
	ds_read_b32 v93, v72 offset:9472
	ds_read_b32 v94, v72 offset:9728
	ds_read_b32 v95, v72 offset:9984
	ds_read_b32 v96, v72 offset:32768
	ds_read_b32 v97, v72 offset:33024
	ds_read_b32 v98, v72 offset:33280
	ds_read_b32 v99, v72 offset:33536
	ds_read_b32 v100, v72 offset:33792
	ds_read_b32 v101, v72 offset:34048
	ds_read_b32 v102, v72 offset:34304
	ds_read_b32 v103, v72 offset:34560
	v_and_b32_e32 v74, 3, v224
	v_bfe_u32 v75, v224, 2, 2
	v_lshrrev_b32_e32 v76, 4, v224
	v_lshlrev_b32_e32 v74, 2, v74
	v_lshl_add_u32 v74, v75, 8, v74
	v_lshl_add_u32 v74, v76, 10, v74
	s_add_i32 s100, s97, 0x0
	v_add_u32_e32 v74, s100, v74
	v_xor_b32_e32 v76, 0, v75
	v_xor_b32_e32 v77, 1, v75
	v_xor_b32_e32 v78, 2, v75
	v_xor_b32_e32 v79, 3, v75
	v_lshl_add_u32 v76, v76, 4, v74
	v_lshl_add_u32 v77, v77, 4, v74
	v_lshl_add_u32 v78, v78, 4, v74
	v_lshl_add_u32 v79, v79, 4, v74
	s_waitcnt lgkmcnt(7)
	v_mov_b32_e32 v104, v80
	v_mul_f32_e32 v105, v104, v81
	v_mul_f32_e32 v106, v105, v82
	v_mul_f32_e32 v107, v106, v83
	v_mul_f32_e32 v108, v107, v84
	v_mul_f32_e32 v109, v108, v85
	v_mul_f32_e32 v110, v109, v86
	v_mul_f32_e32 v111, v110, v87
	v_mov_b32_e32 v112, v88
	v_mul_f32_e32 v113, v104, v89
	v_mul_f32_e32 v114, v105, v90
	v_mul_f32_e32 v115, v106, v91
	v_mul_f32_e32 v116, v107, v92
	v_mul_f32_e32 v117, v108, v93
	v_mul_f32_e32 v118, v109, v94
	v_mul_f32_e32 v119, v110, v95
	v_mul_f32_e32 v120, v104, v96
	s_waitcnt lgkmcnt(0)
	v_mul_f32_e32 v121, v105, v97
	v_mul_f32_e32 v122, v106, v98
	v_mul_f32_e32 v123, v107, v99
	v_mul_f32_e32 v124, v108, v100
	v_mul_f32_e32 v125, v109, v101
	v_mul_f32_e32 v126, v110, v102
	v_mul_f32_e32 v127, v111, v103
	ds_write_b32 v76, v112
	ds_write_b32 v77, v113
	ds_write_b32 v78, v114
	ds_write_b32 v79, v115
	ds_write_b32 v76, v116 offset:64
	ds_write_b32 v77, v117 offset:64
	ds_write_b32 v78, v118 offset:64
	ds_write_b32 v79, v119 offset:64
	ds_write_b32 v76, v120 offset:128
	ds_write_b32 v77, v121 offset:128
	ds_write_b32 v78, v122 offset:128
	ds_write_b32 v79, v123 offset:128
	ds_write_b32 v76, v124 offset:192
	ds_write_b32 v77, v125 offset:192
	ds_write_b32 v78, v126 offset:192
	ds_write_b32 v79, v127 offset:192
